# DFT GEMM epilogue staged through LDS (two 128-row passes) so pq rows and their mirrors are stored as full 512-B rows
# baseline (speedup 1.0000x reference)
; DI int opqv(int x) { asm volatile("" : "+v"(x)); return x; }
; #define EPI_FOR(u) \
;     _Pragma("unroll") for (int ai = 0; ai < 2; ++ai) _Pragma("unroll") for (int m = 0; m < 4; ++m) _Pragma("unroll") for (int bj = 0; bj < 2; ++bj)
; #define EPI_COL(u) (EPI_CB(u) + 8 * fq)
; DI u32x4 pack8(const float* v) { u32x4 w; w.x = pk2(v[0], v[1]); w.y = pk2(v[2], v[3]); w.z = pk2(v[4], v[5]); w.w = pk2(v[6], v[7]); return w; }
;     DI void operator()(const Acc& acc, const Unit& u, int wr, int wc, int fr, int fq) const {
;         const int K384 = opqv(384), K2304 = opqv(DFTR);
;         EPI_FOR(u) {
;             const int row = EPI_ROW(u), col = EPI_COL(u); EPI_V(v);
;             const int type = row >= DFTR, k = row - type * K2304, bl = col / 384, ch = col - bl * K384;
;             if (k <= 2048) {
;                 *(u32x4*)(pq + ((size_t)bl * 4096 + k) * 768 + type * K384 + ch) = pack8(v);
;                 if (k >= 1 && k <= 2047) {
;                     if (type) {
; #pragma unroll
;                         for (int j = 0; j < 8; ++j) v[j] = -v[j];
;                     }
;                     *(u32x4*)(pq + ((size_t)bl * 4096 + (4096 - k)) * 768 + type * K384 + ch) = pack8(v);
;                 }
;             }
;         }
.LBB0_774:
	s_lshl_b32 s2, s14, 8
	s_lshl_b32 s0, s12, 8
	s_cmp_gt_i32 s2, s88
	s_cselect_b32 s8, 1, 0
	s_mul_i32 s9, s8, 0x900
	s_sub_i32 s2, s2, s9
	s_mul_i32 s9, s8, 0x80008000
	v_readfirstlane_b32 s12, v232
	s_lshr_b32 s12, s12, 6
	s_lshl_b32 s12, s12, 4
	v_and_b32_e32 v141, 31, v233
	v_lshl_add_u32 v140, v141, 3, s0
	v_mov_b32_e32 v142, 0x180
	v_cmp_le_u32_e32 vcc, v142, v140
	v_cndmask_b32_e64 v143, 0, 1, vcc
	v_mov_b32_e32 v142, 0x300
	v_cmp_le_u32_e32 vcc, v142, v140
	v_addc_co_u32_e32 v143, vcc, 0, v143, vcc
	v_mov_b32_e32 v142, 0x480
	v_cmp_le_u32_e32 vcc, v142, v140
	v_addc_co_u32_e32 v143, vcc, 0, v143, vcc
	v_mul_u32_u24_e32 v142, 0x180, v143
	v_sub_u32_e32 v140, v140, v142
	s_mul_i32 s13, s8, 0x180
	v_add_u32_e32 v140, s13, v140
	v_mul_u32_u24_e32 v142, 0x300000, v143
	v_add_u32_e32 v140, v142, v140
	v_lshlrev_b32_e32 v140, 1, v140
	v_add_u32_e32 v141, 0x600000, v140
	v_lshrrev_b32_e32 v145, 5, v233
	v_add_u32_e32 v145, s12, v145
	v_mul_u32_u24_e32 v145, 0x210, v145
	v_and_b32_e32 v142, 31, v233
	v_lshl_add_u32 v145, v142, 4, v145
	v_add_u32_e32 v146, s47, v148
	v_mul_u32_u24_e32 v146, 0x210, v146
	v_lshl_add_u32 v142, v149, 3, s48
	v_lshl_add_u32 v146, v142, 1, v146
	s_movk_i32 s13, 0x600
	s_waitcnt vmcnt(0)
	s_barrier
	v_cvt_pk_bf16_f32 v150, v124, v125
	v_cvt_pk_bf16_f32 v151, v126, v127
	v_cvt_pk_bf16_f32 v152, v120, v121
	v_cvt_pk_bf16_f32 v153, v122, v123
	ds_write_b128 v146, v[150:153]
	v_cvt_pk_bf16_f32 v154, v116, v117
	v_cvt_pk_bf16_f32 v155, v118, v119
	v_cvt_pk_bf16_f32 v156, v112, v113
	v_cvt_pk_bf16_f32 v157, v114, v115
	ds_write_b128 v146, v[154:157] offset:256
	v_cvt_pk_bf16_f32 v150, v108, v109
	v_cvt_pk_bf16_f32 v151, v110, v111
	v_cvt_pk_bf16_f32 v152, v104, v105
	v_cvt_pk_bf16_f32 v153, v106, v107
	ds_write_b128 v146, v[150:153] offset:8448
	v_cvt_pk_bf16_f32 v154, v100, v101
	v_cvt_pk_bf16_f32 v155, v102, v103
	v_cvt_pk_bf16_f32 v156, v96, v97
	v_cvt_pk_bf16_f32 v157, v98, v99
	ds_write_b128 v146, v[154:157] offset:8704
	v_cvt_pk_bf16_f32 v150, v92, v93
	v_cvt_pk_bf16_f32 v151, v94, v95
	v_cvt_pk_bf16_f32 v152, v88, v89
	v_cvt_pk_bf16_f32 v153, v90, v91
	ds_write_b128 v146, v[150:153] offset:16896
	v_cvt_pk_bf16_f32 v154, v84, v85
	v_cvt_pk_bf16_f32 v155, v86, v87
	v_cvt_pk_bf16_f32 v156, v80, v81
	v_cvt_pk_bf16_f32 v157, v82, v83
	ds_write_b128 v146, v[154:157] offset:17152
	v_cvt_pk_bf16_f32 v150, v76, v77
	v_cvt_pk_bf16_f32 v151, v78, v79
	v_cvt_pk_bf16_f32 v152, v72, v73
	v_cvt_pk_bf16_f32 v153, v74, v75
	ds_write_b128 v146, v[150:153] offset:25344
	v_cvt_pk_bf16_f32 v154, v68, v69
	v_cvt_pk_bf16_f32 v155, v70, v71
	v_cvt_pk_bf16_f32 v156, v64, v65
	v_cvt_pk_bf16_f32 v157, v66, v67
	ds_write_b128 v146, v[154:157] offset:25600
	s_waitcnt lgkmcnt(0)
	s_barrier
	v_lshrrev_b32_e32 v142, 5, v233
	s_add_i32 s14, s2, 0
	s_add_i32 s14, s14, s12
	v_add_u32_e32 v142, s14, v142
	ds_read_b128 v[158:161], v145
	v_mul_u32_u24_e32 v143, s13, v142
	v_add_u32_e32 v144, v140, v143
	v_sub_u32_e32 v143, v141, v143
	v_cmp_gt_i32_e32 vcc, 0x801, v142
	s_and_saveexec_b64 s[14:15], vcc
	s_waitcnt lgkmcnt(0)
	global_store_dwordx4 v144, v[158:161], s[20:21]
	v_cmp_lt_i32_e32 vcc, 0, v142
	s_and_b64 exec, exec, vcc
	v_cmp_gt_i32_e32 vcc, 0x800, v142
	s_and_b64 exec, exec, vcc
	v_xor_b32_e32 v162, s9, v158
	v_xor_b32_e32 v163, s9, v159
	v_xor_b32_e32 v164, s9, v160
	v_xor_b32_e32 v165, s9, v161
	global_store_dwordx4 v143, v[162:165], s[20:21]
	s_mov_b64 exec, s[14:15]
	v_add_u32_e32 v142, 2, v142
	ds_read_b128 v[158:161], v145 offset:1056
	v_mul_u32_u24_e32 v143, s13, v142
	v_add_u32_e32 v144, v140, v143
	v_sub_u32_e32 v143, v141, v143
	v_cmp_gt_i32_e32 vcc, 0x801, v142
	s_and_saveexec_b64 s[14:15], vcc
	s_waitcnt lgkmcnt(0)
	global_store_dwordx4 v144, v[158:161], s[20:21]
	v_cmp_lt_i32_e32 vcc, 0, v142
	s_and_b64 exec, exec, vcc
	v_cmp_gt_i32_e32 vcc, 0x800, v142
	s_and_b64 exec, exec, vcc
	v_xor_b32_e32 v162, s9, v158
	v_xor_b32_e32 v163, s9, v159
	v_xor_b32_e32 v164, s9, v160
	v_xor_b32_e32 v165, s9, v161
	global_store_dwordx4 v143, v[162:165], s[20:21]
	s_mov_b64 exec, s[14:15]
	v_add_u32_e32 v142, 2, v142
	ds_read_b128 v[158:161], v145 offset:2112
	v_mul_u32_u24_e32 v143, s13, v142
	v_add_u32_e32 v144, v140, v143
	v_sub_u32_e32 v143, v141, v143
	v_cmp_gt_i32_e32 vcc, 0x801, v142
	s_and_saveexec_b64 s[14:15], vcc
	s_waitcnt lgkmcnt(0)
	global_store_dwordx4 v144, v[158:161], s[20:21]
	v_cmp_lt_i32_e32 vcc, 0, v142
	s_and_b64 exec, exec, vcc
	v_cmp_gt_i32_e32 vcc, 0x800, v142
	s_and_b64 exec, exec, vcc
	v_xor_b32_e32 v162, s9, v158
	v_xor_b32_e32 v163, s9, v159
	v_xor_b32_e32 v164, s9, v160
	v_xor_b32_e32 v165, s9, v161
	global_store_dwordx4 v143, v[162:165], s[20:21]
	s_mov_b64 exec, s[14:15]
	v_add_u32_e32 v142, 2, v142
	ds_read_b128 v[158:161], v145 offset:3168
	v_mul_u32_u24_e32 v143, s13, v142
	v_add_u32_e32 v144, v140, v143
	v_sub_u32_e32 v143, v141, v143
	v_cmp_gt_i32_e32 vcc, 0x801, v142
	s_and_saveexec_b64 s[14:15], vcc
	s_waitcnt lgkmcnt(0)
	global_store_dwordx4 v144, v[158:161], s[20:21]
	v_cmp_lt_i32_e32 vcc, 0, v142
	s_and_b64 exec, exec, vcc
	v_cmp_gt_i32_e32 vcc, 0x800, v142
	s_and_b64 exec, exec, vcc
	v_xor_b32_e32 v162, s9, v158
	v_xor_b32_e32 v163, s9, v159
	v_xor_b32_e32 v164, s9, v160
	v_xor_b32_e32 v165, s9, v161
	global_store_dwordx4 v143, v[162:165], s[20:21]
	s_mov_b64 exec, s[14:15]
	v_add_u32_e32 v142, 2, v142
	ds_read_b128 v[158:161], v145 offset:4224
	v_mul_u32_u24_e32 v143, s13, v142
	v_add_u32_e32 v144, v140, v143
	v_sub_u32_e32 v143, v141, v143
	v_cmp_gt_i32_e32 vcc, 0x801, v142
	s_and_saveexec_b64 s[14:15], vcc
	s_waitcnt lgkmcnt(0)
; DI u32x4 pack8(const float* v) { u32x4 w; w.x = pk2(v[0], v[1]); w.y = pk2(v[2], v[3]); w.z = pk2(v[4], v[5]); w.w = pk2(v[6], v[7]); return w; }
;     DI void operator()(const Acc& acc, const Unit& u, int wr, int wc, int fr, int fq) const {
;     ...
;             if (k <= 2048) {
;                 *(u32x4*)(pq + ((size_t)bl * 4096 + k) * 768 + type * K384 + ch) = pack8(v);
;                 if (k >= 1 && k <= 2047) {
;                     if (type) {
; #pragma unroll
;                         for (int j = 0; j < 8; ++j) v[j] = -v[j];
;                     }
;                     *(u32x4*)(pq + ((size_t)bl * 4096 + (4096 - k)) * 768 + type * K384 + ch) = pack8(v);
;                 }
	global_store_dwordx4 v144, v[158:161], s[20:21]
	v_cmp_lt_i32_e32 vcc, 0, v142
	s_and_b64 exec, exec, vcc
	v_cmp_gt_i32_e32 vcc, 0x800, v142
	s_and_b64 exec, exec, vcc
	v_xor_b32_e32 v162, s9, v158
	v_xor_b32_e32 v163, s9, v159
	v_xor_b32_e32 v164, s9, v160
	v_xor_b32_e32 v165, s9, v161
	global_store_dwordx4 v143, v[162:165], s[20:21]
	s_mov_b64 exec, s[14:15]
	v_add_u32_e32 v142, 2, v142
	ds_read_b128 v[158:161], v145 offset:5280
	v_mul_u32_u24_e32 v143, s13, v142
	v_add_u32_e32 v144, v140, v143
	v_sub_u32_e32 v143, v141, v143
	v_cmp_gt_i32_e32 vcc, 0x801, v142
	s_and_saveexec_b64 s[14:15], vcc
	s_waitcnt lgkmcnt(0)
	global_store_dwordx4 v144, v[158:161], s[20:21]
	v_cmp_lt_i32_e32 vcc, 0, v142
	s_and_b64 exec, exec, vcc
	v_cmp_gt_i32_e32 vcc, 0x800, v142
	s_and_b64 exec, exec, vcc
	v_xor_b32_e32 v162, s9, v158
	v_xor_b32_e32 v163, s9, v159
	v_xor_b32_e32 v164, s9, v160
	v_xor_b32_e32 v165, s9, v161
	global_store_dwordx4 v143, v[162:165], s[20:21]
	s_mov_b64 exec, s[14:15]
	v_add_u32_e32 v142, 2, v142
	ds_read_b128 v[158:161], v145 offset:6336
	v_mul_u32_u24_e32 v143, s13, v142
	v_add_u32_e32 v144, v140, v143
	v_sub_u32_e32 v143, v141, v143
	v_cmp_gt_i32_e32 vcc, 0x801, v142
	s_and_saveexec_b64 s[14:15], vcc
	s_waitcnt lgkmcnt(0)
	global_store_dwordx4 v144, v[158:161], s[20:21]
	v_cmp_lt_i32_e32 vcc, 0, v142
	s_and_b64 exec, exec, vcc
	v_cmp_gt_i32_e32 vcc, 0x800, v142
	s_and_b64 exec, exec, vcc
	v_xor_b32_e32 v162, s9, v158
	v_xor_b32_e32 v163, s9, v159
	v_xor_b32_e32 v164, s9, v160
	v_xor_b32_e32 v165, s9, v161
	global_store_dwordx4 v143, v[162:165], s[20:21]
	s_mov_b64 exec, s[14:15]
	v_add_u32_e32 v142, 2, v142
	ds_read_b128 v[158:161], v145 offset:7392
	v_mul_u32_u24_e32 v143, s13, v142
	v_add_u32_e32 v144, v140, v143
	v_sub_u32_e32 v143, v141, v143
	v_cmp_gt_i32_e32 vcc, 0x801, v142
	s_and_saveexec_b64 s[14:15], vcc
	s_waitcnt lgkmcnt(0)
	global_store_dwordx4 v144, v[158:161], s[20:21]
	v_cmp_lt_i32_e32 vcc, 0, v142
	s_and_b64 exec, exec, vcc
	v_cmp_gt_i32_e32 vcc, 0x800, v142
	s_and_b64 exec, exec, vcc
	v_xor_b32_e32 v162, s9, v158
	v_xor_b32_e32 v163, s9, v159
	v_xor_b32_e32 v164, s9, v160
	v_xor_b32_e32 v165, s9, v161
	global_store_dwordx4 v143, v[162:165], s[20:21]
	s_mov_b64 exec, s[14:15]
	v_add_u32_e32 v142, 2, v142
	s_barrier
	v_cvt_pk_bf16_f32 v150, v60, v61
	v_cvt_pk_bf16_f32 v151, v62, v63
	v_cvt_pk_bf16_f32 v152, v56, v57
	v_cvt_pk_bf16_f32 v153, v58, v59
	ds_write_b128 v146, v[150:153]
	v_cvt_pk_bf16_f32 v154, v52, v53
	v_cvt_pk_bf16_f32 v155, v54, v55
	v_cvt_pk_bf16_f32 v156, v48, v49
	v_cvt_pk_bf16_f32 v157, v50, v51
	ds_write_b128 v146, v[154:157] offset:256
	v_cvt_pk_bf16_f32 v150, v44, v45
	v_cvt_pk_bf16_f32 v151, v46, v47
	v_cvt_pk_bf16_f32 v152, v40, v41
	v_cvt_pk_bf16_f32 v153, v42, v43
	ds_write_b128 v146, v[150:153] offset:8448
	v_cvt_pk_bf16_f32 v154, v36, v37
	v_cvt_pk_bf16_f32 v155, v38, v39
	v_cvt_pk_bf16_f32 v156, v32, v33
	v_cvt_pk_bf16_f32 v157, v34, v35
	ds_write_b128 v146, v[154:157] offset:8704
	v_cvt_pk_bf16_f32 v150, v28, v29
	v_cvt_pk_bf16_f32 v151, v30, v31
	v_cvt_pk_bf16_f32 v152, v24, v25
	v_cvt_pk_bf16_f32 v153, v26, v27
	ds_write_b128 v146, v[150:153] offset:16896
	v_cvt_pk_bf16_f32 v154, v20, v21
	v_cvt_pk_bf16_f32 v155, v22, v23
	v_cvt_pk_bf16_f32 v156, v16, v17
	v_cvt_pk_bf16_f32 v157, v18, v19
	ds_write_b128 v146, v[154:157] offset:17152
	v_cvt_pk_bf16_f32 v150, v12, v13
	v_cvt_pk_bf16_f32 v151, v14, v15
	v_cvt_pk_bf16_f32 v152, v8, v9
	v_cvt_pk_bf16_f32 v153, v10, v11
	ds_write_b128 v146, v[150:153] offset:25344
	v_cvt_pk_bf16_f32 v154, v4, v5
	v_cvt_pk_bf16_f32 v155, v6, v7
	v_cvt_pk_bf16_f32 v156, v0, v1
	v_cvt_pk_bf16_f32 v157, v2, v3
	ds_write_b128 v146, v[154:157] offset:25600
	s_waitcnt lgkmcnt(0)
	s_barrier
; DI u32x4 pack8(const float* v) { u32x4 w; w.x = pk2(v[0], v[1]); w.y = pk2(v[2], v[3]); w.z = pk2(v[4], v[5]); w.w = pk2(v[6], v[7]); return w; }
;     DI void operator()(const Acc& acc, const Unit& u, int wr, int wc, int fr, int fq) const {
;     ...
;             if (k <= 2048) {
;                 *(u32x4*)(pq + ((size_t)bl * 4096 + k) * 768 + type * K384 + ch) = pack8(v);
;                 if (k >= 1 && k <= 2047) {
;                     if (type) {
; #pragma unroll
;                         for (int j = 0; j < 8; ++j) v[j] = -v[j];
;                     }
;                     *(u32x4*)(pq + ((size_t)bl * 4096 + (4096 - k)) * 768 + type * K384 + ch) = pack8(v);
;                 }
	v_lshrrev_b32_e32 v142, 5, v233
	s_add_i32 s14, s2, 128
	s_add_i32 s14, s14, s12
	v_add_u32_e32 v142, s14, v142
	ds_read_b128 v[158:161], v145
	v_mul_u32_u24_e32 v143, s13, v142
	v_add_u32_e32 v144, v140, v143
	v_sub_u32_e32 v143, v141, v143
	v_cmp_gt_i32_e32 vcc, 0x801, v142
	s_and_saveexec_b64 s[14:15], vcc
	s_waitcnt lgkmcnt(0)
	global_store_dwordx4 v144, v[158:161], s[20:21]
	v_cmp_lt_i32_e32 vcc, 0, v142
	s_and_b64 exec, exec, vcc
	v_cmp_gt_i32_e32 vcc, 0x800, v142
	s_and_b64 exec, exec, vcc
	v_xor_b32_e32 v162, s9, v158
	v_xor_b32_e32 v163, s9, v159
	v_xor_b32_e32 v164, s9, v160
	v_xor_b32_e32 v165, s9, v161
	global_store_dwordx4 v143, v[162:165], s[20:21]
	s_mov_b64 exec, s[14:15]
	v_add_u32_e32 v142, 2, v142
	ds_read_b128 v[158:161], v145 offset:1056
	v_mul_u32_u24_e32 v143, s13, v142
	v_add_u32_e32 v144, v140, v143
	v_sub_u32_e32 v143, v141, v143
	v_cmp_gt_i32_e32 vcc, 0x801, v142
	s_and_saveexec_b64 s[14:15], vcc
	s_waitcnt lgkmcnt(0)
	global_store_dwordx4 v144, v[158:161], s[20:21]
	v_cmp_lt_i32_e32 vcc, 0, v142
	s_and_b64 exec, exec, vcc
	v_cmp_gt_i32_e32 vcc, 0x800, v142
	s_and_b64 exec, exec, vcc
	v_xor_b32_e32 v162, s9, v158
	v_xor_b32_e32 v163, s9, v159
	v_xor_b32_e32 v164, s9, v160
	v_xor_b32_e32 v165, s9, v161
	global_store_dwordx4 v143, v[162:165], s[20:21]
	s_mov_b64 exec, s[14:15]
	v_add_u32_e32 v142, 2, v142
	ds_read_b128 v[158:161], v145 offset:2112
	v_mul_u32_u24_e32 v143, s13, v142
	v_add_u32_e32 v144, v140, v143
	v_sub_u32_e32 v143, v141, v143
	v_cmp_gt_i32_e32 vcc, 0x801, v142
	s_and_saveexec_b64 s[14:15], vcc
	s_waitcnt lgkmcnt(0)
	global_store_dwordx4 v144, v[158:161], s[20:21]
	v_cmp_lt_i32_e32 vcc, 0, v142
	s_and_b64 exec, exec, vcc
	v_cmp_gt_i32_e32 vcc, 0x800, v142
	s_and_b64 exec, exec, vcc
	v_xor_b32_e32 v162, s9, v158
	v_xor_b32_e32 v163, s9, v159
	v_xor_b32_e32 v164, s9, v160
	v_xor_b32_e32 v165, s9, v161
	global_store_dwordx4 v143, v[162:165], s[20:21]
	s_mov_b64 exec, s[14:15]
	v_add_u32_e32 v142, 2, v142
	ds_read_b128 v[158:161], v145 offset:3168
	v_mul_u32_u24_e32 v143, s13, v142
	v_add_u32_e32 v144, v140, v143
	v_sub_u32_e32 v143, v141, v143
	v_cmp_gt_i32_e32 vcc, 0x801, v142
	s_and_saveexec_b64 s[14:15], vcc
	s_waitcnt lgkmcnt(0)
	global_store_dwordx4 v144, v[158:161], s[20:21]
	v_cmp_lt_i32_e32 vcc, 0, v142
	s_and_b64 exec, exec, vcc
	v_cmp_gt_i32_e32 vcc, 0x800, v142
	s_and_b64 exec, exec, vcc
	v_xor_b32_e32 v162, s9, v158
	v_xor_b32_e32 v163, s9, v159
	v_xor_b32_e32 v164, s9, v160
	v_xor_b32_e32 v165, s9, v161
	global_store_dwordx4 v143, v[162:165], s[20:21]
	s_mov_b64 exec, s[14:15]
	v_add_u32_e32 v142, 2, v142
	ds_read_b128 v[158:161], v145 offset:4224
	v_mul_u32_u24_e32 v143, s13, v142
	v_add_u32_e32 v144, v140, v143
	v_sub_u32_e32 v143, v141, v143
	v_cmp_gt_i32_e32 vcc, 0x801, v142
	s_and_saveexec_b64 s[14:15], vcc
	s_waitcnt lgkmcnt(0)
	global_store_dwordx4 v144, v[158:161], s[20:21]
	v_cmp_lt_i32_e32 vcc, 0, v142
	s_and_b64 exec, exec, vcc
	v_cmp_gt_i32_e32 vcc, 0x800, v142
	s_and_b64 exec, exec, vcc
	v_xor_b32_e32 v162, s9, v158
	v_xor_b32_e32 v163, s9, v159
	v_xor_b32_e32 v164, s9, v160
	v_xor_b32_e32 v165, s9, v161
	global_store_dwordx4 v143, v[162:165], s[20:21]
	s_mov_b64 exec, s[14:15]
	v_add_u32_e32 v142, 2, v142
	ds_read_b128 v[158:161], v145 offset:5280
	v_mul_u32_u24_e32 v143, s13, v142
	v_add_u32_e32 v144, v140, v143
	v_sub_u32_e32 v143, v141, v143
	v_cmp_gt_i32_e32 vcc, 0x801, v142
	s_and_saveexec_b64 s[14:15], vcc
	s_waitcnt lgkmcnt(0)
	global_store_dwordx4 v144, v[158:161], s[20:21]
	v_cmp_lt_i32_e32 vcc, 0, v142
	s_and_b64 exec, exec, vcc
	v_cmp_gt_i32_e32 vcc, 0x800, v142
	s_and_b64 exec, exec, vcc
	v_xor_b32_e32 v162, s9, v158
	v_xor_b32_e32 v163, s9, v159
	v_xor_b32_e32 v164, s9, v160
	v_xor_b32_e32 v165, s9, v161
	global_store_dwordx4 v143, v[162:165], s[20:21]
	s_mov_b64 exec, s[14:15]
	v_add_u32_e32 v142, 2, v142
	ds_read_b128 v[158:161], v145 offset:6336
	v_mul_u32_u24_e32 v143, s13, v142
	v_add_u32_e32 v144, v140, v143
	v_sub_u32_e32 v143, v141, v143
	v_cmp_gt_i32_e32 vcc, 0x801, v142
	s_and_saveexec_b64 s[14:15], vcc
	s_waitcnt lgkmcnt(0)
	global_store_dwordx4 v144, v[158:161], s[20:21]
	v_cmp_lt_i32_e32 vcc, 0, v142
	s_and_b64 exec, exec, vcc
	v_cmp_gt_i32_e32 vcc, 0x800, v142
	s_and_b64 exec, exec, vcc
	v_xor_b32_e32 v162, s9, v158
	v_xor_b32_e32 v163, s9, v159
	v_xor_b32_e32 v164, s9, v160
	v_xor_b32_e32 v165, s9, v161
	global_store_dwordx4 v143, v[162:165], s[20:21]
	s_mov_b64 exec, s[14:15]
	v_add_u32_e32 v142, 2, v142
	ds_read_b128 v[158:161], v145 offset:7392
	v_mul_u32_u24_e32 v143, s13, v142
	v_add_u32_e32 v144, v140, v143
	v_sub_u32_e32 v143, v141, v143
	v_cmp_gt_i32_e32 vcc, 0x801, v142
	s_and_saveexec_b64 s[14:15], vcc
	s_waitcnt lgkmcnt(0)
	global_store_dwordx4 v144, v[158:161], s[20:21]
	v_cmp_lt_i32_e32 vcc, 0, v142
	s_and_b64 exec, exec, vcc
	v_cmp_gt_i32_e32 vcc, 0x800, v142
	s_and_b64 exec, exec, vcc
	v_xor_b32_e32 v162, s9, v158
	v_xor_b32_e32 v163, s9, v159
	v_xor_b32_e32 v164, s9, v160
	v_xor_b32_e32 v165, s9, v161
	global_store_dwordx4 v143, v[162:165], s[20:21]
	s_mov_b64 exec, s[14:15]
	v_add_u32_e32 v142, 2, v142
	s_mov_b64 s[6:7], exec
